# v4_guepi
# speedup vs baseline: 1.0119x; 1.0119x over previous
; __device__ void attn_item(const Params& P, int item, u16* shm, int wid_s) {
;     ...
;     if (active && qmax > kb * 64) {
;     ...
;     int done = 1;
;     if (active) done = (carry[0] < -110.f) && (carry[1] < -110.f) && (carry[2] < -110.f) && (carry[3] < -110.f);
;     const bool wdone = __builtin_amdgcn_ballot_w64(!done) == 0ull;
.LBB0_161:
	v_cmp_ngt_f32_e32 vcc, s18, v36
	v_cmp_ngt_f32_e64 s[6:7], s18, v37
	s_or_b64 s[8:9], vcc, s[6:7]
	v_cmp_ngt_f32_e32 vcc, s18, v38
	v_cmp_ngt_f32_e64 s[6:7], s18, v39
	s_or_b64 s[8:9], s[8:9], vcc
	s_or_b64 s[8:9], s[8:9], s[6:7]
	s_cmp_lg_u64 s[8:9], 0
	s_cselect_b64 s[8:9], -1, 0
	v_cmp_lt_i32_e32 vcc, s35, v86
	s_and_b64 s[6:7], s[0:1], vcc
	s_and_b64 s[6:7], s[6:7], s[8:9]
	s_and_saveexec_b64 s[20:21], s[6:7]
	s_cbranch_execz .LBB0_239
	s_add_i32 s6, s35, 48
	v_cmp_ge_u32_e32 vcc, s6, v86
	s_and_saveexec_b64 s[6:7], vcc
	s_xor_b64 s[6:7], exec, s[6:7]
	s_cbranch_execz .LBB0_164
	ds_write_b16 v97, v1 offset:35936
	ds_write_b16 v97, v1 offset:36080
	ds_write_b16 v97, v1 offset:36224

; __device__ __forceinline__ float fdiv(float a, float b) { return a * __builtin_amdgcn_rcpf(b); }
; __device__ __forceinline__ void gemm_tile(const Params& P, const GArgs& ga, const TileDesc& td, int wid_s) {
;     ...
;   if (mode == M_GU) {
;     LOAD_RSV
;     unsigned* __restrict__ G = reinterpret_cast<unsigned*>(WSU(G) + (size_t)rbase * FF + (bcol >> 1) + (x4 >> 1));
;     static_for<32>([&](auto ic) __attribute__((always_inline)) {
;       EPI_IDX;
;       const float rs = rsv[idx];
;       float g0 = rs * acc[ai][0][m][0][j], u0 = rs * acc[ai][0][m][1][j];
;       float g1 = rs * acc[ai][1][m][0][j], u1 = rs * acc[ai][1][m][1][j];
;       __builtin_nontemporal_store(pack2(fdiv(g0 * u0, 1.f + __expf(-g0)), fdiv(g1 * u1, 1.f + __expf(-g1))), G + (size_t)rl * (FF / 2));
;       if constexpr ((idx & 7) == 7) __builtin_amdgcn_sched_barrier(0);
;     });
.LBB0_748:
	s_and_b64 vcc, exec, s[84:85]
	s_cbranch_vccz .LBB0_290
	v_lshl_add_u64 v[194:195], v[166:167], 2, s[72:73]
	global_load_dwordx4 v[130:133], v[194:195], off
	global_load_dwordx4 v[134:137], v[194:195], off offset:64
	global_load_dwordx4 v[138:141], v[194:195], off offset:128
	global_load_dwordx4 v[142:145], v[194:195], off offset:192
	global_load_dwordx4 v[146:149], v[194:195], off offset:512
	global_load_dwordx4 v[150:153], v[194:195], off offset:576
	global_load_dwordx4 v[154:157], v[194:195], off offset:640
	global_load_dwordx4 v[158:161], v[194:195], off offset:704
	v_and_b32_e32 v196, 15, v200
	v_and_b32_e32 v197, 0xc0, v200
	v_lshl_or_b32 v196, v196, 2, v197
	s_lshl_b32 s0, s15, 8
	v_mov_b32_e32 v197, 0x2c00
	v_mad_u32_u24 v196, v166, v197, v196
	v_mov_b32_e32 v198, s17
	v_add_u32_e32 v196, s0, v196
	s_waitcnt vmcnt(7)
	v_fmamk_f32 v130, v130, 0x3a000000, v198
	v_fmamk_f32 v131, v131, 0x3a000000, v198
	v_fmamk_f32 v132, v132, 0x3a000000, v198
	v_fmamk_f32 v133, v133, 0x3a000000, v198
	v_rsq_f32_e32 v162, v130
	v_rsq_f32_e32 v163, v131
	v_rsq_f32_e32 v164, v132
	v_rsq_f32_e32 v165, v133
	s_waitcnt vmcnt(6)
	v_fmamk_f32 v134, v134, 0x3a000000, v198
	v_fmamk_f32 v135, v135, 0x3a000000, v198
	v_fmamk_f32 v136, v136, 0x3a000000, v198
	v_fmamk_f32 v137, v137, 0x3a000000, v198
	v_rsq_f32_e32 v166, v134
	v_rsq_f32_e32 v167, v135
	v_rsq_f32_e32 v168, v136
	v_rsq_f32_e32 v169, v137
	v_mul_f32_e32 v162, 0xbfb8aa3b, v162
	v_mul_f32_e32 v163, 0xbfb8aa3b, v163
	v_mul_f32_e32 v164, 0xbfb8aa3b, v164
	v_mul_f32_e32 v165, 0xbfb8aa3b, v165
	s_waitcnt vmcnt(5)
	v_fmamk_f32 v138, v138, 0x3a000000, v198
	v_fmamk_f32 v139, v139, 0x3a000000, v198
	v_fmamk_f32 v140, v140, 0x3a000000, v198
	v_fmamk_f32 v141, v141, 0x3a000000, v198
	v_rsq_f32_e32 v170, v138
	v_rsq_f32_e32 v171, v139
	v_rsq_f32_e32 v172, v140
	v_rsq_f32_e32 v173, v141
	v_mul_f32_e32 v166, 0xbfb8aa3b, v166
	v_mul_f32_e32 v167, 0xbfb8aa3b, v167
	v_mul_f32_e32 v168, 0xbfb8aa3b, v168
	v_mul_f32_e32 v169, 0xbfb8aa3b, v169
	s_waitcnt vmcnt(4)
	v_fmamk_f32 v142, v142, 0x3a000000, v198
	v_fmamk_f32 v143, v143, 0x3a000000, v198
	v_fmamk_f32 v144, v144, 0x3a000000, v198
	v_fmamk_f32 v145, v145, 0x3a000000, v198
	v_rsq_f32_e32 v174, v142
	v_rsq_f32_e32 v175, v143
	v_rsq_f32_e32 v176, v144
	v_rsq_f32_e32 v177, v145
	v_mul_f32_e32 v170, 0xbfb8aa3b, v170
	v_mul_f32_e32 v171, 0xbfb8aa3b, v171
	v_mul_f32_e32 v172, 0xbfb8aa3b, v172
	v_mul_f32_e32 v173, 0xbfb8aa3b, v173
	s_waitcnt vmcnt(3)
	v_fmamk_f32 v146, v146, 0x3a000000, v198
	v_fmamk_f32 v147, v147, 0x3a000000, v198
	v_fmamk_f32 v148, v148, 0x3a000000, v198
	v_fmamk_f32 v149, v149, 0x3a000000, v198
	v_rsq_f32_e32 v178, v146
	v_rsq_f32_e32 v179, v147
	v_rsq_f32_e32 v180, v148
	v_rsq_f32_e32 v181, v149
	v_mul_f32_e32 v174, 0xbfb8aa3b, v174
	v_mul_f32_e32 v175, 0xbfb8aa3b, v175
	v_mul_f32_e32 v176, 0xbfb8aa3b, v176
	v_mul_f32_e32 v177, 0xbfb8aa3b, v177
	s_waitcnt vmcnt(2)
	v_fmamk_f32 v150, v150, 0x3a000000, v198
	v_fmamk_f32 v151, v151, 0x3a000000, v198
	v_fmamk_f32 v152, v152, 0x3a000000, v198
	v_fmamk_f32 v153, v153, 0x3a000000, v198
	v_rsq_f32_e32 v182, v150
	v_rsq_f32_e32 v183, v151
	v_rsq_f32_e32 v184, v152
	v_rsq_f32_e32 v185, v153
	v_mul_f32_e32 v178, 0xbfb8aa3b, v178
	v_mul_f32_e32 v179, 0xbfb8aa3b, v179
	v_mul_f32_e32 v180, 0xbfb8aa3b, v180
	v_mul_f32_e32 v181, 0xbfb8aa3b, v181
	s_waitcnt vmcnt(1)
	v_fmamk_f32 v154, v154, 0x3a000000, v198
	v_fmamk_f32 v155, v155, 0x3a000000, v198
	v_fmamk_f32 v156, v156, 0x3a000000, v198
	v_fmamk_f32 v157, v157, 0x3a000000, v198
	v_rsq_f32_e32 v186, v154
	v_rsq_f32_e32 v187, v155
	v_rsq_f32_e32 v188, v156
	v_rsq_f32_e32 v189, v157
	v_mul_f32_e32 v182, 0xbfb8aa3b, v182
	v_mul_f32_e32 v183, 0xbfb8aa3b, v183
	v_mul_f32_e32 v184, 0xbfb8aa3b, v184
	v_mul_f32_e32 v185, 0xbfb8aa3b, v185
	s_waitcnt vmcnt(0)
	v_fmamk_f32 v158, v158, 0x3a000000, v198
	v_fmamk_f32 v159, v159, 0x3a000000, v198
	v_fmamk_f32 v160, v160, 0x3a000000, v198
	v_fmamk_f32 v161, v161, 0x3a000000, v198
	v_rsq_f32_e32 v190, v158
	v_rsq_f32_e32 v191, v159
	v_rsq_f32_e32 v192, v160
	v_rsq_f32_e32 v193, v161
	v_mul_f32_e32 v186, 0xbfb8aa3b, v186
	v_mul_f32_e32 v187, 0xbfb8aa3b, v187
	v_mul_f32_e32 v188, 0xbfb8aa3b, v188
	v_mul_f32_e32 v189, 0xbfb8aa3b, v189
	s_nop 0
	v_mul_f32_e32 v190, 0xbfb8aa3b, v190
	v_mul_f32_e32 v191, 0xbfb8aa3b, v191
	v_mul_f32_e32 v192, 0xbfb8aa3b, v192
	v_mul_f32_e32 v193, 0xbfb8aa3b, v193
	v_mul_f32_e32 v204, v114, v162
	v_mul_f32_e32 v205, v126, v162
	v_mul_f32_e32 v206, v115, v163
	v_mul_f32_e32 v207, v127, v163
	v_mul_f32_e32 v208, v116, v164
	v_mul_f32_e32 v209, v128, v164
	v_mul_f32_e32 v210, v117, v165
	v_mul_f32_e32 v211, v129, v165
	v_exp_f32_e32 v204, v204
	v_exp_f32_e32 v205, v205
	v_exp_f32_e32 v206, v206
	v_exp_f32_e32 v207, v207
	v_exp_f32_e32 v208, v208
	v_exp_f32_e32 v209, v209
	v_exp_f32_e32 v210, v210
	v_exp_f32_e32 v211, v211
	v_mul_f32_e32 v212, v114, v118
	v_mul_f32_e32 v213, v126, v122
	v_mul_f32_e32 v214, v115, v119
	v_mul_f32_e32 v215, v127, v123
	v_mul_f32_e32 v216, v116, v120
	v_mul_f32_e32 v217, v128, v124
	v_mul_f32_e32 v218, v117, v121
	v_mul_f32_e32 v219, v129, v125
	v_fma_f32 v204, v204, v130, v130
	v_fma_f32 v205, v205, v130, v130
	v_fma_f32 v206, v206, v131, v131
	v_fma_f32 v207, v207, v131, v131
	v_fma_f32 v208, v208, v132, v132
	v_fma_f32 v209, v209, v132, v132
	v_fma_f32 v210, v210, v133, v133
	v_fma_f32 v211, v211, v133, v133
	v_rcp_f32_e32 v204, v204
	v_rcp_f32_e32 v205, v205
	v_rcp_f32_e32 v206, v206
	v_rcp_f32_e32 v207, v207
	v_rcp_f32_e32 v208, v208
	v_rcp_f32_e32 v209, v209
	v_rcp_f32_e32 v210, v210
	v_rcp_f32_e32 v211, v211
	v_mul_f32_e32 v212, v212, v204
	v_mul_f32_e32 v213, v213, v205
; __device__ __forceinline__ float fdiv(float a, float b) { return a * __builtin_amdgcn_rcpf(b); }
; __device__ __forceinline__ void gemm_tile(const Params& P, const GArgs& ga, const TileDesc& td, int wid_s) {
;     ...
;     static_for<32>([&](auto ic) __attribute__((always_inline)) {
;       EPI_IDX;
;       const float rs = rsv[idx];
;       float g0 = rs * acc[ai][0][m][0][j], u0 = rs * acc[ai][0][m][1][j];
;       float g1 = rs * acc[ai][1][m][0][j], u1 = rs * acc[ai][1][m][1][j];
;       __builtin_nontemporal_store(pack2(fdiv(g0 * u0, 1.f + __expf(-g0)), fdiv(g1 * u1, 1.f + __expf(-g1))), G + (size_t)rl * (FF / 2));
;       if constexpr ((idx & 7) == 7) __builtin_amdgcn_sched_barrier(0);
;     });
	v_mul_f32_e32 v214, v214, v206
	v_mul_f32_e32 v215, v215, v207
	s_add_u32 s4, s24, 0x0
	s_addc_u32 s5, s25, 0
	v_mul_f32_e32 v216, v216, v208
	v_mul_f32_e32 v217, v217, v209
	v_mul_f32_e32 v218, v218, v210
	v_mul_f32_e32 v219, v219, v211
	v_cvt_pk_bf16_f32 v220, v212, v213
	v_cvt_pk_bf16_f32 v221, v214, v215
	v_cvt_pk_bf16_f32 v222, v216, v217
	v_cvt_pk_bf16_f32 v223, v218, v219
	global_store_dword v196, v220, s[4:5] nt
	s_add_u32 s4, s4, 0x2c00
	s_addc_u32 s5, s5, 0
	global_store_dword v196, v221, s[4:5] nt
	s_add_u32 s4, s4, 0x2c00
	s_addc_u32 s5, s5, 0
	global_store_dword v196, v222, s[4:5] nt
	s_add_u32 s4, s4, 0x2c00
	s_addc_u32 s5, s5, 0
	global_store_dword v196, v223, s[4:5] nt
	v_mul_f32_e32 v204, v98, v166
	v_mul_f32_e32 v205, v110, v166
	v_mul_f32_e32 v206, v99, v167
	v_mul_f32_e32 v207, v111, v167
	v_mul_f32_e32 v208, v100, v168
	v_mul_f32_e32 v209, v112, v168
	v_mul_f32_e32 v210, v101, v169
	v_mul_f32_e32 v211, v113, v169
	v_exp_f32_e32 v204, v204
	v_exp_f32_e32 v205, v205
	v_exp_f32_e32 v206, v206
	v_exp_f32_e32 v207, v207
	v_exp_f32_e32 v208, v208
	v_exp_f32_e32 v209, v209
	v_exp_f32_e32 v210, v210
	v_exp_f32_e32 v211, v211
	v_mul_f32_e32 v212, v98, v102
	v_mul_f32_e32 v213, v110, v106
	v_mul_f32_e32 v214, v99, v103
	v_mul_f32_e32 v215, v111, v107
	v_mul_f32_e32 v216, v100, v104
	v_mul_f32_e32 v217, v112, v108
	v_mul_f32_e32 v218, v101, v105
	v_mul_f32_e32 v219, v113, v109
	v_fma_f32 v204, v204, v134, v134
	v_fma_f32 v205, v205, v134, v134
	v_fma_f32 v206, v206, v135, v135
	v_fma_f32 v207, v207, v135, v135
	v_fma_f32 v208, v208, v136, v136
	v_fma_f32 v209, v209, v136, v136
	v_fma_f32 v210, v210, v137, v137
	v_fma_f32 v211, v211, v137, v137
	v_rcp_f32_e32 v204, v204
	v_rcp_f32_e32 v205, v205
	v_rcp_f32_e32 v206, v206
	v_rcp_f32_e32 v207, v207
	v_rcp_f32_e32 v208, v208
	v_rcp_f32_e32 v209, v209
	v_rcp_f32_e32 v210, v210
	v_rcp_f32_e32 v211, v211
	v_mul_f32_e32 v212, v212, v204
	v_mul_f32_e32 v213, v213, v205
	v_mul_f32_e32 v214, v214, v206
	v_mul_f32_e32 v215, v215, v207
	s_add_u32 s4, s24, 0x2c000
	s_addc_u32 s5, s25, 0
	v_mul_f32_e32 v216, v216, v208
	v_mul_f32_e32 v217, v217, v209
	v_mul_f32_e32 v218, v218, v210
	v_mul_f32_e32 v219, v219, v211
	v_cvt_pk_bf16_f32 v220, v212, v213
	v_cvt_pk_bf16_f32 v221, v214, v215
	v_cvt_pk_bf16_f32 v222, v216, v217
	v_cvt_pk_bf16_f32 v223, v218, v219
	global_store_dword v196, v220, s[4:5] nt
	s_add_u32 s4, s4, 0x2c00
	s_addc_u32 s5, s5, 0
	global_store_dword v196, v221, s[4:5] nt
	s_add_u32 s4, s4, 0x2c00
	s_addc_u32 s5, s5, 0
	global_store_dword v196, v222, s[4:5] nt
	s_add_u32 s4, s4, 0x2c00
	s_addc_u32 s5, s5, 0
	global_store_dword v196, v223, s[4:5] nt
	v_mul_f32_e32 v204, v82, v170
	v_mul_f32_e32 v205, v94, v170
	v_mul_f32_e32 v206, v83, v171
	v_mul_f32_e32 v207, v95, v171
	v_mul_f32_e32 v208, v84, v172
	v_mul_f32_e32 v209, v96, v172
	v_mul_f32_e32 v210, v85, v173
	v_mul_f32_e32 v211, v97, v173
	v_exp_f32_e32 v204, v204
	v_exp_f32_e32 v205, v205
	v_exp_f32_e32 v206, v206
	v_exp_f32_e32 v207, v207
	v_exp_f32_e32 v208, v208
	v_exp_f32_e32 v209, v209
	v_exp_f32_e32 v210, v210
	v_exp_f32_e32 v211, v211
	v_mul_f32_e32 v212, v82, v86
	v_mul_f32_e32 v213, v94, v90
	v_mul_f32_e32 v214, v83, v87
	v_mul_f32_e32 v215, v95, v91
	v_mul_f32_e32 v216, v84, v88
	v_mul_f32_e32 v217, v96, v92
	v_mul_f32_e32 v218, v85, v89
	v_mul_f32_e32 v219, v97, v93
	v_fma_f32 v204, v204, v138, v138
	v_fma_f32 v205, v205, v138, v138
	v_fma_f32 v206, v206, v139, v139
	v_fma_f32 v207, v207, v139, v139
	v_fma_f32 v208, v208, v140, v140
	v_fma_f32 v209, v209, v140, v140
	v_fma_f32 v210, v210, v141, v141
	v_fma_f32 v211, v211, v141, v141
	v_rcp_f32_e32 v204, v204
	v_rcp_f32_e32 v205, v205
	v_rcp_f32_e32 v206, v206
	v_rcp_f32_e32 v207, v207
	v_rcp_f32_e32 v208, v208
	v_rcp_f32_e32 v209, v209
	v_rcp_f32_e32 v210, v210
	v_rcp_f32_e32 v211, v211
	v_mul_f32_e32 v212, v212, v204
	v_mul_f32_e32 v213, v213, v205
	v_mul_f32_e32 v214, v214, v206
	v_mul_f32_e32 v215, v215, v207
	s_add_u32 s4, s24, 0x58000
	s_addc_u32 s5, s25, 0
	v_mul_f32_e32 v216, v216, v208
	v_mul_f32_e32 v217, v217, v209
	v_mul_f32_e32 v218, v218, v210
	v_mul_f32_e32 v219, v219, v211
	v_cvt_pk_bf16_f32 v220, v212, v213
	v_cvt_pk_bf16_f32 v221, v214, v215
	v_cvt_pk_bf16_f32 v222, v216, v217
	v_cvt_pk_bf16_f32 v223, v218, v219
	global_store_dword v196, v220, s[4:5] nt
	s_add_u32 s4, s4, 0x2c00
	s_addc_u32 s5, s5, 0
	global_store_dword v196, v221, s[4:5] nt
	s_add_u32 s4, s4, 0x2c00
	s_addc_u32 s5, s5, 0
	global_store_dword v196, v222, s[4:5] nt
	s_add_u32 s4, s4, 0x2c00
	s_addc_u32 s5, s5, 0
	global_store_dword v196, v223, s[4:5] nt
	v_mul_f32_e32 v204, v66, v174
	v_mul_f32_e32 v205, v78, v174
	v_mul_f32_e32 v206, v67, v175
	v_mul_f32_e32 v207, v79, v175
	v_mul_f32_e32 v208, v68, v176
	v_mul_f32_e32 v209, v80, v176
	v_mul_f32_e32 v210, v69, v177
	v_mul_f32_e32 v211, v81, v177
	v_exp_f32_e32 v204, v204
	v_exp_f32_e32 v205, v205
	v_exp_f32_e32 v206, v206
	v_exp_f32_e32 v207, v207
	v_exp_f32_e32 v208, v208
	v_exp_f32_e32 v209, v209
	v_exp_f32_e32 v210, v210
	v_exp_f32_e32 v211, v211
	v_mul_f32_e32 v212, v66, v70
	v_mul_f32_e32 v213, v78, v74
	v_mul_f32_e32 v214, v67, v71
	v_mul_f32_e32 v215, v79, v75
	v_mul_f32_e32 v216, v68, v72
	v_mul_f32_e32 v217, v80, v76
	v_mul_f32_e32 v218, v69, v73
	v_mul_f32_e32 v219, v81, v77
	v_fma_f32 v204, v204, v142, v142
	v_fma_f32 v205, v205, v142, v142
	v_fma_f32 v206, v206, v143, v143
	v_fma_f32 v207, v207, v143, v143
	v_fma_f32 v208, v208, v144, v144
	v_fma_f32 v209, v209, v144, v144
	v_fma_f32 v210, v210, v145, v145
	v_fma_f32 v211, v211, v145, v145
	v_rcp_f32_e32 v204, v204
	v_rcp_f32_e32 v205, v205
	v_rcp_f32_e32 v206, v206
; __device__ __forceinline__ float fdiv(float a, float b) { return a * __builtin_amdgcn_rcpf(b); }
; __device__ __forceinline__ void gemm_tile(const Params& P, const GArgs& ga, const TileDesc& td, int wid_s) {
;     ...
;     static_for<32>([&](auto ic) __attribute__((always_inline)) {
;       EPI_IDX;
;       const float rs = rsv[idx];
;       float g0 = rs * acc[ai][0][m][0][j], u0 = rs * acc[ai][0][m][1][j];
;       float g1 = rs * acc[ai][1][m][0][j], u1 = rs * acc[ai][1][m][1][j];
;       __builtin_nontemporal_store(pack2(fdiv(g0 * u0, 1.f + __expf(-g0)), fdiv(g1 * u1, 1.f + __expf(-g1))), G + (size_t)rl * (FF / 2));
;       if constexpr ((idx & 7) == 7) __builtin_amdgcn_sched_barrier(0);
;     });
	v_rcp_f32_e32 v207, v207
	v_rcp_f32_e32 v208, v208
	v_rcp_f32_e32 v209, v209
	v_rcp_f32_e32 v210, v210
	v_rcp_f32_e32 v211, v211
	v_mul_f32_e32 v212, v212, v204
	v_mul_f32_e32 v213, v213, v205
	v_mul_f32_e32 v214, v214, v206
	v_mul_f32_e32 v215, v215, v207
	s_add_u32 s4, s24, 0x84000
	s_addc_u32 s5, s25, 0
	v_mul_f32_e32 v216, v216, v208
	v_mul_f32_e32 v217, v217, v209
	v_mul_f32_e32 v218, v218, v210
	v_mul_f32_e32 v219, v219, v211
	v_cvt_pk_bf16_f32 v220, v212, v213
	v_cvt_pk_bf16_f32 v221, v214, v215
	v_cvt_pk_bf16_f32 v222, v216, v217
	v_cvt_pk_bf16_f32 v223, v218, v219
	global_store_dword v196, v220, s[4:5] nt
	s_add_u32 s4, s4, 0x2c00
	s_addc_u32 s5, s5, 0
	global_store_dword v196, v221, s[4:5] nt
	s_add_u32 s4, s4, 0x2c00
	s_addc_u32 s5, s5, 0
	global_store_dword v196, v222, s[4:5] nt
	s_add_u32 s4, s4, 0x2c00
	s_addc_u32 s5, s5, 0
	global_store_dword v196, v223, s[4:5] nt
	v_mul_f32_e32 v204, v50, v178
	v_mul_f32_e32 v205, v62, v178
	v_mul_f32_e32 v206, v51, v179
	v_mul_f32_e32 v207, v63, v179
	v_mul_f32_e32 v208, v52, v180
	v_mul_f32_e32 v209, v64, v180
	v_mul_f32_e32 v210, v53, v181
	v_mul_f32_e32 v211, v65, v181
	v_exp_f32_e32 v204, v204
	v_exp_f32_e32 v205, v205
	v_exp_f32_e32 v206, v206
	v_exp_f32_e32 v207, v207
	v_exp_f32_e32 v208, v208
	v_exp_f32_e32 v209, v209
	v_exp_f32_e32 v210, v210
	v_exp_f32_e32 v211, v211
	v_mul_f32_e32 v212, v50, v54
	v_mul_f32_e32 v213, v62, v58
	v_mul_f32_e32 v214, v51, v55
	v_mul_f32_e32 v215, v63, v59
	v_mul_f32_e32 v216, v52, v56
	v_mul_f32_e32 v217, v64, v60
	v_mul_f32_e32 v218, v53, v57
	v_mul_f32_e32 v219, v65, v61
	v_fma_f32 v204, v204, v146, v146
	v_fma_f32 v205, v205, v146, v146
	v_fma_f32 v206, v206, v147, v147
	v_fma_f32 v207, v207, v147, v147
	v_fma_f32 v208, v208, v148, v148
	v_fma_f32 v209, v209, v148, v148
	v_fma_f32 v210, v210, v149, v149
	v_fma_f32 v211, v211, v149, v149
	v_rcp_f32_e32 v204, v204
	v_rcp_f32_e32 v205, v205
	v_rcp_f32_e32 v206, v206
	v_rcp_f32_e32 v207, v207
	v_rcp_f32_e32 v208, v208
	v_rcp_f32_e32 v209, v209
	v_rcp_f32_e32 v210, v210
	v_rcp_f32_e32 v211, v211
	v_mul_f32_e32 v212, v212, v204
	v_mul_f32_e32 v213, v213, v205
	v_mul_f32_e32 v214, v214, v206
	v_mul_f32_e32 v215, v215, v207
	s_add_u32 s4, s24, 0x160000
	s_addc_u32 s5, s25, 0
	v_mul_f32_e32 v216, v216, v208
	v_mul_f32_e32 v217, v217, v209
	v_mul_f32_e32 v218, v218, v210
	v_mul_f32_e32 v219, v219, v211
	v_cvt_pk_bf16_f32 v220, v212, v213
	v_cvt_pk_bf16_f32 v221, v214, v215
	v_cvt_pk_bf16_f32 v222, v216, v217
	v_cvt_pk_bf16_f32 v223, v218, v219
	global_store_dword v196, v220, s[4:5] nt
	s_add_u32 s4, s4, 0x2c00
	s_addc_u32 s5, s5, 0
	global_store_dword v196, v221, s[4:5] nt
	s_add_u32 s4, s4, 0x2c00
	s_addc_u32 s5, s5, 0
	global_store_dword v196, v222, s[4:5] nt
	s_add_u32 s4, s4, 0x2c00
	s_addc_u32 s5, s5, 0
	global_store_dword v196, v223, s[4:5] nt
	v_mul_f32_e32 v204, v34, v182
	v_mul_f32_e32 v205, v46, v182
	v_mul_f32_e32 v206, v35, v183
	v_mul_f32_e32 v207, v47, v183
	v_mul_f32_e32 v208, v36, v184
	v_mul_f32_e32 v209, v48, v184
	v_mul_f32_e32 v210, v37, v185
	v_mul_f32_e32 v211, v49, v185
	v_exp_f32_e32 v204, v204
	v_exp_f32_e32 v205, v205
	v_exp_f32_e32 v206, v206
	v_exp_f32_e32 v207, v207
	v_exp_f32_e32 v208, v208
	v_exp_f32_e32 v209, v209
	v_exp_f32_e32 v210, v210
	v_exp_f32_e32 v211, v211
	v_mul_f32_e32 v212, v34, v38
	v_mul_f32_e32 v213, v46, v42
	v_mul_f32_e32 v214, v35, v39
	v_mul_f32_e32 v215, v47, v43
	v_mul_f32_e32 v216, v36, v40
	v_mul_f32_e32 v217, v48, v44
	v_mul_f32_e32 v218, v37, v41
	v_mul_f32_e32 v219, v49, v45
	v_fma_f32 v204, v204, v150, v150
	v_fma_f32 v205, v205, v150, v150
	v_fma_f32 v206, v206, v151, v151
	v_fma_f32 v207, v207, v151, v151
	v_fma_f32 v208, v208, v152, v152
	v_fma_f32 v209, v209, v152, v152
	v_fma_f32 v210, v210, v153, v153
	v_fma_f32 v211, v211, v153, v153
	v_rcp_f32_e32 v204, v204
	v_rcp_f32_e32 v205, v205
	v_rcp_f32_e32 v206, v206
	v_rcp_f32_e32 v207, v207
	v_rcp_f32_e32 v208, v208
	v_rcp_f32_e32 v209, v209
	v_rcp_f32_e32 v210, v210
	v_rcp_f32_e32 v211, v211
	v_mul_f32_e32 v212, v212, v204
	v_mul_f32_e32 v213, v213, v205
	v_mul_f32_e32 v214, v214, v206
	v_mul_f32_e32 v215, v215, v207
	s_add_u32 s4, s24, 0x18c000
	s_addc_u32 s5, s25, 0
	v_mul_f32_e32 v216, v216, v208
	v_mul_f32_e32 v217, v217, v209
	v_mul_f32_e32 v218, v218, v210
	v_mul_f32_e32 v219, v219, v211
; __device__ __forceinline__ float fdiv(float a, float b) { return a * __builtin_amdgcn_rcpf(b); }
; __device__ __forceinline__ void gemm_tile(const Params& P, const GArgs& ga, const TileDesc& td, int wid_s) {
;     ...
;     static_for<32>([&](auto ic) __attribute__((always_inline)) {
;       EPI_IDX;
;       const float rs = rsv[idx];
;       float g0 = rs * acc[ai][0][m][0][j], u0 = rs * acc[ai][0][m][1][j];
;       float g1 = rs * acc[ai][1][m][0][j], u1 = rs * acc[ai][1][m][1][j];
;       __builtin_nontemporal_store(pack2(fdiv(g0 * u0, 1.f + __expf(-g0)), fdiv(g1 * u1, 1.f + __expf(-g1))), G + (size_t)rl * (FF / 2));
;       if constexpr ((idx & 7) == 7) __builtin_amdgcn_sched_barrier(0);
;     });
	v_cvt_pk_bf16_f32 v220, v212, v213
	v_cvt_pk_bf16_f32 v221, v214, v215
	v_cvt_pk_bf16_f32 v222, v216, v217
	v_cvt_pk_bf16_f32 v223, v218, v219
	global_store_dword v196, v220, s[4:5] nt
	s_add_u32 s4, s4, 0x2c00
	s_addc_u32 s5, s5, 0
	global_store_dword v196, v221, s[4:5] nt
	s_add_u32 s4, s4, 0x2c00
	s_addc_u32 s5, s5, 0
	global_store_dword v196, v222, s[4:5] nt
	s_add_u32 s4, s4, 0x2c00
	s_addc_u32 s5, s5, 0
	global_store_dword v196, v223, s[4:5] nt
	v_mul_f32_e32 v204, v18, v186
	v_mul_f32_e32 v205, v30, v186
	v_mul_f32_e32 v206, v19, v187
	v_mul_f32_e32 v207, v31, v187
	v_mul_f32_e32 v208, v20, v188
	v_mul_f32_e32 v209, v32, v188
	v_mul_f32_e32 v210, v21, v189
	v_mul_f32_e32 v211, v33, v189
	v_exp_f32_e32 v204, v204
	v_exp_f32_e32 v205, v205
	v_exp_f32_e32 v206, v206
	v_exp_f32_e32 v207, v207
	v_exp_f32_e32 v208, v208
	v_exp_f32_e32 v209, v209
	v_exp_f32_e32 v210, v210
	v_exp_f32_e32 v211, v211
	v_mul_f32_e32 v212, v18, v22
	v_mul_f32_e32 v213, v30, v26
	v_mul_f32_e32 v214, v19, v23
	v_mul_f32_e32 v215, v31, v27
	v_mul_f32_e32 v216, v20, v24
	v_mul_f32_e32 v217, v32, v28
	v_mul_f32_e32 v218, v21, v25
	v_mul_f32_e32 v219, v33, v29
	v_fma_f32 v204, v204, v154, v154
	v_fma_f32 v205, v205, v154, v154
	v_fma_f32 v206, v206, v155, v155
	v_fma_f32 v207, v207, v155, v155
	v_fma_f32 v208, v208, v156, v156
	v_fma_f32 v209, v209, v156, v156
	v_fma_f32 v210, v210, v157, v157
	v_fma_f32 v211, v211, v157, v157
	v_rcp_f32_e32 v204, v204
	v_rcp_f32_e32 v205, v205
	v_rcp_f32_e32 v206, v206
	v_rcp_f32_e32 v207, v207
	v_rcp_f32_e32 v208, v208
	v_rcp_f32_e32 v209, v209
	v_rcp_f32_e32 v210, v210
	v_rcp_f32_e32 v211, v211
	v_mul_f32_e32 v212, v212, v204
	v_mul_f32_e32 v213, v213, v205
	v_mul_f32_e32 v214, v214, v206
	v_mul_f32_e32 v215, v215, v207
	s_add_u32 s4, s24, 0x1b8000
	s_addc_u32 s5, s25, 0
	v_mul_f32_e32 v216, v216, v208
	v_mul_f32_e32 v217, v217, v209
	v_mul_f32_e32 v218, v218, v210
	v_mul_f32_e32 v219, v219, v211
	v_cvt_pk_bf16_f32 v220, v212, v213
	v_cvt_pk_bf16_f32 v221, v214, v215
	v_cvt_pk_bf16_f32 v222, v216, v217
	v_cvt_pk_bf16_f32 v223, v218, v219
	global_store_dword v196, v220, s[4:5] nt
	s_add_u32 s4, s4, 0x2c00
	s_addc_u32 s5, s5, 0
	global_store_dword v196, v221, s[4:5] nt
	s_add_u32 s4, s4, 0x2c00
	s_addc_u32 s5, s5, 0
	global_store_dword v196, v222, s[4:5] nt
	s_add_u32 s4, s4, 0x2c00
	s_addc_u32 s5, s5, 0
	global_store_dword v196, v223, s[4:5] nt
	v_mul_f32_e32 v204, v2, v190
	v_mul_f32_e32 v205, v14, v190
	v_mul_f32_e32 v206, v3, v191
	v_mul_f32_e32 v207, v15, v191
	v_mul_f32_e32 v208, v4, v192
	v_mul_f32_e32 v209, v16, v192
	v_mul_f32_e32 v210, v5, v193
	v_mul_f32_e32 v211, v17, v193
	v_exp_f32_e32 v204, v204
	v_exp_f32_e32 v205, v205
	v_exp_f32_e32 v206, v206
	v_exp_f32_e32 v207, v207
	v_exp_f32_e32 v208, v208
	v_exp_f32_e32 v209, v209
	v_exp_f32_e32 v210, v210
	v_exp_f32_e32 v211, v211
	v_mul_f32_e32 v212, v2, v6
	v_mul_f32_e32 v213, v14, v10
	v_mul_f32_e32 v214, v3, v7
	v_mul_f32_e32 v215, v15, v11
	v_mul_f32_e32 v216, v4, v8
	v_mul_f32_e32 v217, v16, v12
	v_mul_f32_e32 v218, v5, v9
	v_mul_f32_e32 v219, v17, v13
	v_fma_f32 v204, v204, v158, v158
	v_fma_f32 v205, v205, v158, v158
	v_fma_f32 v206, v206, v159, v159
	v_fma_f32 v207, v207, v159, v159
	v_fma_f32 v208, v208, v160, v160
	v_fma_f32 v209, v209, v160, v160
	v_fma_f32 v210, v210, v161, v161
	v_fma_f32 v211, v211, v161, v161
	v_rcp_f32_e32 v204, v204
	v_rcp_f32_e32 v205, v205
	v_rcp_f32_e32 v206, v206
	v_rcp_f32_e32 v207, v207
	v_rcp_f32_e32 v208, v208
	v_rcp_f32_e32 v209, v209
	v_rcp_f32_e32 v210, v210
	v_rcp_f32_e32 v211, v211
	v_mul_f32_e32 v212, v212, v204
	v_mul_f32_e32 v213, v213, v205
	v_mul_f32_e32 v214, v214, v206
	v_mul_f32_e32 v215, v215, v207
	s_add_u32 s4, s24, 0x1e4000
	s_addc_u32 s5, s25, 0
	v_mul_f32_e32 v216, v216, v208
	v_mul_f32_e32 v217, v217, v209
	v_mul_f32_e32 v218, v218, v210
	v_mul_f32_e32 v219, v219, v211
	v_cvt_pk_bf16_f32 v220, v212, v213
	v_cvt_pk_bf16_f32 v221, v214, v215
	v_cvt_pk_bf16_f32 v222, v216, v217
	v_cvt_pk_bf16_f32 v223, v218, v219
	global_store_dword v196, v220, s[4:5] nt
	s_add_u32 s4, s4, 0x2c00
	s_addc_u32 s5, s5, 0
	global_store_dword v196, v221, s[4:5] nt
	s_add_u32 s4, s4, 0x2c00
	s_addc_u32 s5, s5, 0
	global_store_dword v196, v222, s[4:5] nt
	s_add_u32 s4, s4, 0x2c00
	s_addc_u32 s5, s5, 0
	global_store_dword v196, v223, s[4:5] nt
	s_branch .LBB0_290
